# nontemporal hints on single-use streams: f32 residual loads in the GOUT epilogue, f32 output stores in the FFN2 epilogue
# speedup vs baseline: 1.0000x; 1.0000x over previous
.LBB0_1342:
	s_lshl_b32 s0, s67, 8
	v_mov_b32_e32 v142, v147
	v_mov_b32_e32 v153, v146
	s_add_i32 s0, s0, s52
	s_lshl_b32 s34, s14, 2
	v_add_u32_e32 v144, s0, v142
	s_lshl_b32 s0, s14, 8
	s_or_b32 s0, s0, s53
	v_lshl_add_u32 v142, v153, 3, s0
	v_ashrrev_i32_e32 v145, 31, v144
	v_ashrrev_i32_e32 v143, 31, v142
	v_lshlrev_b64 v[154:155], 11, v[144:145]
	v_lshl_add_u64 v[162:163], v[154:155], 0, v[142:143]
	s_waitcnt lgkmcnt(0)
	v_lshl_add_u64 v[164:165], v[162:163], 2, s[12:13]
	v_mov_b32_e32 v170, v164
	v_mov_b32_e32 v171, v165
	global_load_dwordx4 v[172:175], v[170:171], off nt
	global_load_dwordx4 v[176:179], v[170:171], off offset:16 nt
	global_load_dwordx4 v[180:183], v[170:171], off offset:512 nt
	global_load_dwordx4 v[184:187], v[170:171], off offset:528 nt
	s_mov_b64 s[98:99], 0x20000
	v_lshl_add_u64 v[170:171], v[170:171], 0, s[98:99]
	global_load_dwordx4 v[188:191], v[170:171], off nt
	global_load_dwordx4 v[192:195], v[170:171], off offset:16 nt
	global_load_dwordx4 v[196:199], v[170:171], off offset:512 nt
	global_load_dwordx4 v[200:203], v[170:171], off offset:528 nt
	s_mov_b64 s[98:99], 0x20000
	v_lshl_add_u64 v[170:171], v[170:171], 0, s[98:99]
	global_load_dwordx4 v[204:207], v[170:171], off nt
	global_load_dwordx4 v[208:211], v[170:171], off offset:16 nt
	global_load_dwordx4 v[212:215], v[170:171], off offset:512 nt
	global_load_dwordx4 v[216:219], v[170:171], off offset:528 nt
	s_mov_b64 s[98:99], 0x20000
	v_lshl_add_u64 v[170:171], v[170:171], 0, s[98:99]
	global_load_dwordx4 v[220:223], v[170:171], off nt
	global_load_dwordx4 v[224:227], v[170:171], off offset:16 nt
	global_load_dwordx4 v[232:235], v[170:171], off offset:512 nt
	global_load_dwordx4 v[236:239], v[170:171], off offset:528 nt
	s_mov_b64 s[98:99], 0xa0000
	v_lshl_add_u64 v[170:171], v[170:171], 0, s[98:99]
	global_load_dwordx4 v[240:243], v[170:171], off nt
	global_load_dwordx4 v[244:247], v[170:171], off offset:16 nt
	global_load_dwordx4 v[248:251], v[170:171], off offset:512 nt
	global_load_dwordx4 v[252:255], v[170:171], off offset:528 nt
	s_waitcnt vmcnt(19)
	s_nop 1
	v_mov_b32_e32 v154, v172
	v_mov_b32_e32 v155, v173
	v_mov_b32_e32 v156, v174
	v_mov_b32_e32 v157, v175
	s_mov_b64 s[98:99], 0x20000
	v_lshl_add_u64 v[170:171], v[170:171], 0, s[98:99]
	global_load_dwordx4 v[172:175], v[170:171], off nt
	s_waitcnt vmcnt(19)
	s_nop 1
	v_mov_b32_e32 v158, v176
	v_mov_b32_e32 v159, v177
	v_mov_b32_e32 v160, v178
	v_mov_b32_e32 v161, v179
	global_load_dwordx4 v[176:179], v[170:171], off offset:16 nt
	v_lshl_add_u64 v[162:163], v[162:163], 1, s[18:19]
	s_ashr_i32 s35, s34, 31
	s_nop 0
	v_pk_add_f32 v[166:167], v[122:123], v[156:157]
	v_pk_add_f32 v[168:169], v[120:121], v[154:155]
	v_pk_add_f32 v[126:127], v[126:127], v[160:161]
	v_pk_add_f32 v[158:159], v[124:125], v[158:159]
	v_cvt_pk_bf16_f32 v120, v168, v169
	v_cvt_pk_bf16_f32 v121, v166, v167
	v_mul_f32_e32 v161, v169, v169
	v_cvt_pk_bf16_f32 v122, v158, v159
	v_cvt_pk_bf16_f32 v123, v126, v127
	global_store_dwordx4 v[162:163], v[120:123], off
	s_waitcnt vmcnt(20)
	s_nop 1
	v_mov_b32_e32 v122, v180
	v_mov_b32_e32 v123, v181
	v_mov_b32_e32 v124, v182
	v_mov_b32_e32 v125, v183
	global_load_dwordx4 v[180:183], v[170:171], off offset:512 nt
	s_nop 0
	s_waitcnt vmcnt(20)
	s_nop 1
	v_mov_b32_e32 v154, v184
	v_mov_b32_e32 v155, v185
	v_mov_b32_e32 v156, v186
	v_mov_b32_e32 v157, v187
	global_load_dwordx4 v[184:187], v[170:171], off offset:528 nt
	v_mul_f32_e32 v164, v167, v167
	v_and_b32_e32 v121, 64, v152
	v_mul_f32_e32 v159, v159, v159
	v_mul_f32_e32 v127, v127, v127
	v_fmac_f32_e32 v161, v168, v168
	v_fmac_f32_e32 v164, v166, v166
	v_xor_b32_e32 v120, 16, v152
	v_add_u32_e32 v121, 64, v121
	v_fmac_f32_e32 v159, v158, v158
	v_fmac_f32_e32 v127, v126, v126
	v_add_f32_e32 v126, v161, v164
	v_cmp_lt_i32_e32 vcc, v120, v121
	v_add_f32_e32 v126, v126, v159
	v_add_f32_e32 v126, v127, v126
	v_cndmask_b32_e32 v120, v152, v120, vcc
	v_lshlrev_b32_e32 v120, 2, v120
	v_xor_b32_e32 v160, 32, v152
	v_cmp_lt_i32_e64 s[4:5], v160, v121
	v_cmp_eq_u32_e32 vcc, 0, v153
	s_nop 0
	v_pk_add_f32 v[118:119], v[118:119], v[124:125]
	v_pk_add_f32 v[116:117], v[116:117], v[122:123]
	s_nop 0
	v_pk_add_f32 v[124:125], v[112:113], v[154:155]
	v_mul_f32_e32 v112, v117, v117
	v_mul_f32_e32 v113, v119, v119
	v_pk_add_f32 v[122:123], v[114:115], v[156:157]
	v_mul_f32_e32 v114, v125, v125
	v_fmac_f32_e32 v112, v116, v116
	v_fmac_f32_e32 v113, v118, v118
	v_mul_f32_e32 v115, v123, v123
	v_fmac_f32_e32 v114, v124, v124
	v_add_f32_e32 v112, v112, v113
	v_fmac_f32_e32 v115, v122, v122
	v_add_f32_e32 v112, v112, v114
	v_add_f32_e32 v112, v115, v112
	v_add_f32_e32 v112, v126, v112
	ds_bpermute_b32 v113, v120, v112
	v_cndmask_b32_e64 v114, v152, v160, s[4:5]
	v_lshlrev_b32_e32 v114, 2, v114
	v_cvt_pk_bf16_f32 v116, v116, v117
	v_cvt_pk_bf16_f32 v117, v118, v119
	s_waitcnt lgkmcnt(0)
	v_add_f32_e32 v112, v112, v113
	ds_bpermute_b32 v113, v114, v112
	v_cvt_pk_bf16_f32 v118, v124, v125
	v_cvt_pk_bf16_f32 v119, v122, v123
	global_store_dwordx4 v[162:163], v[116:119], off offset:256
	s_and_saveexec_b64 s[4:5], vcc
	s_cbranch_execz .LBB0_1344
	v_lshlrev_b64 v[116:117], 7, v[144:145]
	v_lshl_add_u64 v[116:117], s[20:21], 0, v[116:117]
	v_lshl_add_u64 v[116:117], s[34:35], 2, v[116:117]
	s_lshl_b32 s14, s50, 2
	v_lshl_add_u64 v[116:117], v[116:117], 0, s[14:15]
	s_waitcnt lgkmcnt(0)
	v_add_f32_e32 v112, v112, v113
	global_store_dword v[116:117], v112, off
.LBB0_1344:
	s_or_b64 exec, exec, s[4:5]
	v_add_u32_e32 v112, 16, v144
	s_waitcnt lgkmcnt(0)
	v_ashrrev_i32_e32 v113, 31, v112
	v_lshlrev_b64 v[116:117], 11, v[112:113]
	v_lshl_add_u64 v[126:127], v[116:117], 0, v[142:143]
	v_lshl_add_u64 v[154:155], v[126:127], 2, s[12:13]
	s_waitcnt vmcnt(21)
	s_nop 1
	v_mov_b32_e32 v116, v188
	v_mov_b32_e32 v117, v189
	v_mov_b32_e32 v118, v190
	v_mov_b32_e32 v119, v191
	s_mov_b64 s[98:99], 0x20000
	v_lshl_add_u64 v[170:171], v[170:171], 0, s[98:99]
	global_load_dwordx4 v[188:191], v[170:171], off nt
	s_waitcnt vmcnt(21)
	s_nop 1
	v_mov_b32_e32 v122, v192
	v_mov_b32_e32 v123, v193
	v_mov_b32_e32 v124, v194
	v_mov_b32_e32 v125, v195
	global_load_dwordx4 v[192:195], v[170:171], off offset:16 nt
	v_lshl_add_u64 v[126:127], v[126:127], 1, s[18:19]
	s_nop 0
	v_pk_add_f32 v[118:119], v[110:111], v[118:119]
	v_pk_add_f32 v[116:117], v[108:109], v[116:117]
	s_nop 0
	v_pk_add_f32 v[124:125], v[106:107], v[124:125]
	v_pk_add_f32 v[122:123], v[104:105], v[122:123]
	v_cvt_pk_bf16_f32 v104, v116, v117
	v_cvt_pk_bf16_f32 v105, v118, v119
	v_mul_f32_e32 v115, v117, v117
	v_cvt_pk_bf16_f32 v106, v122, v123
	v_cvt_pk_bf16_f32 v107, v124, v125
	global_store_dwordx4 v[126:127], v[104:107], off
	s_waitcnt vmcnt(22)
	s_nop 1
	v_mov_b32_e32 v104, v196
	v_mov_b32_e32 v105, v197
	v_mov_b32_e32 v106, v198
	v_mov_b32_e32 v107, v199
	global_load_dwordx4 v[196:199], v[170:171], off offset:512 nt
	s_nop 0
	s_waitcnt vmcnt(22)
	s_nop 1
	v_mov_b32_e32 v108, v200
	v_mov_b32_e32 v109, v201
	v_mov_b32_e32 v110, v202
	v_mov_b32_e32 v111, v203
	global_load_dwordx4 v[200:203], v[170:171], off offset:528 nt
	v_mul_f32_e32 v117, v119, v119
	v_mul_f32_e32 v119, v123, v123
	v_fmac_f32_e32 v115, v116, v116
	v_fmac_f32_e32 v117, v118, v118
	v_mul_f32_e32 v121, v125, v125
	v_fmac_f32_e32 v119, v122, v122
	v_add_f32_e32 v115, v115, v117
	v_fmac_f32_e32 v121, v124, v124
	v_add_f32_e32 v115, v115, v119
	v_add_f32_e32 v115, v121, v115
	s_nop 0
	v_pk_add_f32 v[102:103], v[102:103], v[106:107]
	v_pk_add_f32 v[100:101], v[100:101], v[104:105]
	s_nop 0
	v_pk_add_f32 v[106:107], v[96:97], v[108:109]
	v_mul_f32_e32 v96, v101, v101
	v_mul_f32_e32 v97, v103, v103
	v_pk_add_f32 v[104:105], v[98:99], v[110:111]
	v_mul_f32_e32 v98, v107, v107
	v_fmac_f32_e32 v96, v100, v100
	v_fmac_f32_e32 v97, v102, v102
	v_mul_f32_e32 v99, v105, v105
	v_fmac_f32_e32 v98, v106, v106
	v_add_f32_e32 v96, v96, v97
	v_add_f32_e32 v96, v96, v98
	v_fmac_f32_e32 v99, v104, v104
	v_add_f32_e32 v96, v99, v96
	v_add_f32_e32 v96, v115, v96
	ds_bpermute_b32 v97, v120, v96
	v_cvt_pk_bf16_f32 v98, v100, v101
	v_cvt_pk_bf16_f32 v99, v102, v103
	v_cvt_pk_bf16_f32 v100, v106, v107
	v_cvt_pk_bf16_f32 v101, v104, v105
	s_waitcnt lgkmcnt(0)
	v_add_f32_e32 v96, v96, v97
	ds_bpermute_b32 v97, v114, v96
	global_store_dwordx4 v[126:127], v[98:101], off offset:256
	s_and_saveexec_b64 s[4:5], vcc
	s_cbranch_execz .LBB0_1346
	v_lshlrev_b64 v[98:99], 7, v[112:113]
	v_lshl_add_u64 v[98:99], s[20:21], 0, v[98:99]
	v_lshl_add_u64 v[98:99], s[34:35], 2, v[98:99]
	s_lshl_b32 s14, s50, 2
	v_lshl_add_u64 v[98:99], v[98:99], 0, s[14:15]
	s_waitcnt lgkmcnt(0)
	v_add_f32_e32 v96, v96, v97
	global_store_dword v[98:99], v96, off
.LBB0_1346:
	s_or_b64 exec, exec, s[4:5]
	v_add_u32_e32 v96, 32, v144
	s_waitcnt lgkmcnt(0)
	v_ashrrev_i32_e32 v97, 31, v96
	v_lshlrev_b64 v[98:99], 11, v[96:97]
	v_lshl_add_u64 v[106:107], v[98:99], 0, v[142:143]
	v_lshl_add_u64 v[108:109], v[106:107], 2, s[12:13]
	s_waitcnt vmcnt(23)
	s_nop 1
	v_mov_b32_e32 v98, v204
	v_mov_b32_e32 v99, v205
	v_mov_b32_e32 v100, v206
	v_mov_b32_e32 v101, v207
	s_mov_b64 s[98:99], 0x20000
	v_lshl_add_u64 v[170:171], v[170:171], 0, s[98:99]
	global_load_dwordx4 v[204:207], v[170:171], off nt
	s_waitcnt vmcnt(23)
	s_nop 1
	v_mov_b32_e32 v102, v208
	v_mov_b32_e32 v103, v209
	v_mov_b32_e32 v104, v210
	v_mov_b32_e32 v105, v211
	global_load_dwordx4 v[208:211], v[170:171], off offset:16 nt
	v_lshl_add_u64 v[106:107], v[106:107], 1, s[18:19]
	s_nop 0
	v_pk_add_f32 v[100:101], v[94:95], v[100:101]
	v_pk_add_f32 v[98:99], v[92:93], v[98:99]
	s_nop 0
	v_pk_add_f32 v[104:105], v[90:91], v[104:105]
	v_pk_add_f32 v[102:103], v[88:89], v[102:103]
	v_cvt_pk_bf16_f32 v88, v98, v99
	v_cvt_pk_bf16_f32 v89, v100, v101
	v_mul_f32_e32 v99, v99, v99
	v_cvt_pk_bf16_f32 v90, v102, v103
	v_cvt_pk_bf16_f32 v91, v104, v105
	global_store_dwordx4 v[106:107], v[88:91], off
	s_waitcnt vmcnt(24)
	s_nop 1
	v_mov_b32_e32 v88, v212
	v_mov_b32_e32 v89, v213
	v_mov_b32_e32 v90, v214
	v_mov_b32_e32 v91, v215
	global_load_dwordx4 v[212:215], v[170:171], off offset:512 nt
	s_nop 0
	s_waitcnt vmcnt(24)
	s_nop 1
	v_mov_b32_e32 v92, v216
	v_mov_b32_e32 v93, v217
	v_mov_b32_e32 v94, v218
	v_mov_b32_e32 v95, v219
	global_load_dwordx4 v[216:219], v[170:171], off offset:528 nt
	v_mul_f32_e32 v101, v101, v101
	v_mul_f32_e32 v103, v103, v103
	v_fmac_f32_e32 v99, v98, v98
	v_fmac_f32_e32 v101, v100, v100
	v_mul_f32_e32 v105, v105, v105
	v_fmac_f32_e32 v103, v102, v102
	v_add_f32_e32 v98, v99, v101
	v_fmac_f32_e32 v105, v104, v104
	v_add_f32_e32 v98, v98, v103
	v_add_f32_e32 v98, v105, v98
	s_nop 0
	v_pk_add_f32 v[86:87], v[86:87], v[90:91]
	v_pk_add_f32 v[84:85], v[84:85], v[88:89]
	s_nop 0
	v_pk_add_f32 v[90:91], v[80:81], v[92:93]
	v_mul_f32_e32 v80, v85, v85
	v_mul_f32_e32 v81, v87, v87
	v_pk_add_f32 v[88:89], v[82:83], v[94:95]
	v_mul_f32_e32 v82, v91, v91
	v_fmac_f32_e32 v80, v84, v84
	v_fmac_f32_e32 v81, v86, v86
	v_mul_f32_e32 v83, v89, v89
	v_fmac_f32_e32 v82, v90, v90
	v_add_f32_e32 v80, v80, v81
	v_add_f32_e32 v80, v80, v82
	v_fmac_f32_e32 v83, v88, v88
	v_add_f32_e32 v80, v83, v80
	v_add_f32_e32 v80, v98, v80
	ds_bpermute_b32 v81, v120, v80
	v_cvt_pk_bf16_f32 v82, v84, v85
	v_cvt_pk_bf16_f32 v83, v86, v87
	v_cvt_pk_bf16_f32 v84, v90, v91
	v_cvt_pk_bf16_f32 v85, v88, v89
	s_waitcnt lgkmcnt(0)
	v_add_f32_e32 v80, v80, v81
	ds_bpermute_b32 v81, v114, v80
	global_store_dwordx4 v[106:107], v[82:85], off offset:256
	s_and_saveexec_b64 s[4:5], vcc
	s_cbranch_execz .LBB0_1348
	v_lshlrev_b64 v[82:83], 7, v[96:97]
	v_lshl_add_u64 v[82:83], s[20:21], 0, v[82:83]
	v_lshl_add_u64 v[82:83], s[34:35], 2, v[82:83]
	s_lshl_b32 s14, s50, 2
	v_lshl_add_u64 v[82:83], v[82:83], 0, s[14:15]
	s_waitcnt lgkmcnt(0)
	v_add_f32_e32 v80, v80, v81
	global_store_dword v[82:83], v80, off

.LBB0_1577:
	v_mov_b32_e32 v138, v141
	v_mov_b32_e32 v139, v140
	s_lshl_b32 s33, s72, 8
	s_add_i32 s33, s33, s63
	v_add_u32_e32 v138, s33, v138
	s_lshl_b32 s33, s71, 8
	s_or_b32 s33, s33, s64
	v_lshl_add_u32 v146, v139, 2, s33
	v_ashrrev_i32_e32 v139, 31, v138
	v_ashrrev_i32_e32 v147, 31, v146
	v_lshlrev_b64 v[138:139], 11, v[138:139]
	v_lshl_add_u64 v[138:139], v[138:139], 0, v[146:147]
	v_lshl_add_u64 v[146:147], v[138:139], 1, s[14:15]
	v_mov_b32_e32 v154, v146
	v_mov_b32_e32 v155, v147
	global_load_dwordx2 v[156:157], v[154:155], off
	global_load_dwordx2 v[158:159], v[154:155], off offset:32
	global_load_dwordx2 v[160:161], v[154:155], off offset:256
	global_load_dwordx2 v[162:163], v[154:155], off offset:288
	s_mov_b64 s[98:99], 0x10000
	v_lshl_add_u64 v[154:155], v[154:155], 0, s[98:99]
	global_load_dwordx2 v[164:165], v[154:155], off
	global_load_dwordx2 v[166:167], v[154:155], off offset:32
	global_load_dwordx2 v[168:169], v[154:155], off offset:256
	global_load_dwordx2 v[170:171], v[154:155], off offset:288
	s_mov_b64 s[98:99], 0x10000
	v_lshl_add_u64 v[154:155], v[154:155], 0, s[98:99]
	global_load_dwordx2 v[172:173], v[154:155], off
	global_load_dwordx2 v[174:175], v[154:155], off offset:32
	global_load_dwordx2 v[176:177], v[154:155], off offset:256
	global_load_dwordx2 v[178:179], v[154:155], off offset:288
	s_mov_b64 s[98:99], 0x10000
	v_lshl_add_u64 v[154:155], v[154:155], 0, s[98:99]
	global_load_dwordx2 v[180:181], v[154:155], off
	global_load_dwordx2 v[182:183], v[154:155], off offset:32
	global_load_dwordx2 v[184:185], v[154:155], off offset:256
	global_load_dwordx2 v[186:187], v[154:155], off offset:288
	s_mov_b64 s[98:99], 0x50000
	v_lshl_add_u64 v[154:155], v[154:155], 0, s[98:99]
	global_load_dwordx2 v[188:189], v[154:155], off
	global_load_dwordx2 v[190:191], v[154:155], off offset:32
	global_load_dwordx2 v[192:193], v[154:155], off offset:256
	global_load_dwordx2 v[194:195], v[154:155], off offset:288
	s_mov_b64 s[98:99], 0x10000
	v_lshl_add_u64 v[154:155], v[154:155], 0, s[98:99]
	global_load_dwordx2 v[196:197], v[154:155], off
	global_load_dwordx2 v[198:199], v[154:155], off offset:32
	global_load_dwordx2 v[200:201], v[154:155], off offset:256
	global_load_dwordx2 v[202:203], v[154:155], off offset:288
	s_mov_b64 s[98:99], 0x10000
	v_lshl_add_u64 v[154:155], v[154:155], 0, s[98:99]
	global_load_dwordx2 v[204:205], v[154:155], off
	global_load_dwordx2 v[206:207], v[154:155], off offset:32
	global_load_dwordx2 v[208:209], v[154:155], off offset:256
	global_load_dwordx2 v[210:211], v[154:155], off offset:288
	s_mov_b64 s[98:99], 0x10000
	v_lshl_add_u64 v[154:155], v[154:155], 0, s[98:99]
	global_load_dwordx2 v[212:213], v[154:155], off
	global_load_dwordx2 v[214:215], v[154:155], off offset:32
	global_load_dwordx2 v[216:217], v[154:155], off offset:256
	global_load_dwordx2 v[218:219], v[154:155], off offset:288
	s_waitcnt vmcnt(31)
	s_nop 1
	v_mov_b32_e32 v148, v156
	v_mov_b32_e32 v149, v157
	v_lshl_add_u64 v[150:151], v[138:139], 2, s[4:5]
	s_and_b64 vcc, exec, s[0:1]
	s_mov_b64 s[0:1], -1
	s_nop 0
	v_lshlrev_b32_e32 v152, 16, v148
	v_and_b32_e32 v153, 0xffff0000, v148
	v_lshlrev_b32_e32 v148, 16, v149
	v_and_b32_e32 v149, 0xffff0000, v149
	v_pk_add_f32 v[126:127], v[126:127], v[148:149]
	v_pk_add_f32 v[124:125], v[124:125], v[152:153]
	global_store_dwordx4 v[150:151], v[124:127], off nt
	s_waitcnt vmcnt(31)
	s_nop 1
	v_mov_b32_e32 v124, v158
	v_mov_b32_e32 v125, v159
	s_nop 0
	v_lshlrev_b32_e32 v126, 16, v124
	v_and_b32_e32 v127, 0xffff0000, v124
	v_lshlrev_b32_e32 v124, 16, v125
	v_and_b32_e32 v125, 0xffff0000, v125
	v_pk_add_f32 v[122:123], v[122:123], v[124:125]
	v_pk_add_f32 v[120:121], v[120:121], v[126:127]
	global_store_dwordx4 v[150:151], v[120:123], off offset:64 nt
	s_waitcnt vmcnt(31)
	s_nop 1
	v_mov_b32_e32 v120, v160
	v_mov_b32_e32 v121, v161
	s_nop 0
	v_lshlrev_b32_e32 v122, 16, v120
	v_and_b32_e32 v123, 0xffff0000, v120
	v_lshlrev_b32_e32 v120, 16, v121
	v_and_b32_e32 v121, 0xffff0000, v121
	v_pk_add_f32 v[118:119], v[118:119], v[120:121]
	v_pk_add_f32 v[116:117], v[116:117], v[122:123]
	global_store_dwordx4 v[150:151], v[116:119], off offset:512 nt
	s_waitcnt vmcnt(31)
	s_nop 1
	v_mov_b32_e32 v116, v162
	v_mov_b32_e32 v117, v163
	s_nop 0
	v_lshlrev_b32_e32 v122, 16, v116
	v_and_b32_e32 v123, 0xffff0000, v116
	v_lshlrev_b32_e32 v116, 16, v117
	v_and_b32_e32 v117, 0xffff0000, v117
	v_lshl_add_u64 v[118:119], v[138:139], 0, s[22:23]
	v_pk_add_f32 v[114:115], v[114:115], v[116:117]
	v_pk_add_f32 v[112:113], v[112:113], v[122:123]
	v_lshl_add_u64 v[120:121], v[118:119], 1, s[14:15]
	global_store_dwordx4 v[150:151], v[112:115], off offset:576 nt
	s_waitcnt vmcnt(31)
	s_nop 1
	v_mov_b32_e32 v112, v164
	v_mov_b32_e32 v113, v165
	s_nop 0
	v_lshlrev_b32_e32 v116, 16, v112
	v_and_b32_e32 v117, 0xffff0000, v112
	v_lshlrev_b32_e32 v112, 16, v113
	v_and_b32_e32 v113, 0xffff0000, v113
	v_lshl_add_u64 v[114:115], v[118:119], 2, s[4:5]
	v_pk_add_f32 v[110:111], v[110:111], v[112:113]
	v_pk_add_f32 v[108:109], v[108:109], v[116:117]
	global_store_dwordx4 v[114:115], v[108:111], off nt
	s_waitcnt vmcnt(31)
	s_nop 1
	v_mov_b32_e32 v108, v166
	v_mov_b32_e32 v109, v167
	s_nop 0
	v_lshlrev_b32_e32 v110, 16, v108
	v_and_b32_e32 v111, 0xffff0000, v108
	v_lshlrev_b32_e32 v108, 16, v109
	v_and_b32_e32 v109, 0xffff0000, v109
	v_pk_add_f32 v[106:107], v[106:107], v[108:109]
	v_pk_add_f32 v[104:105], v[104:105], v[110:111]
	global_store_dwordx4 v[114:115], v[104:107], off offset:64 nt
	s_waitcnt vmcnt(31)
	s_nop 1
	v_mov_b32_e32 v104, v168
	v_mov_b32_e32 v105, v169
	s_nop 0
	v_lshlrev_b32_e32 v106, 16, v104
	v_and_b32_e32 v107, 0xffff0000, v104
	v_lshlrev_b32_e32 v104, 16, v105
	v_and_b32_e32 v105, 0xffff0000, v105
	v_pk_add_f32 v[102:103], v[102:103], v[104:105]
	v_pk_add_f32 v[100:101], v[100:101], v[106:107]
	global_store_dwordx4 v[114:115], v[100:103], off offset:512 nt
	s_waitcnt vmcnt(31)
	s_nop 1
	v_mov_b32_e32 v100, v170
	v_mov_b32_e32 v101, v171
	s_nop 0
	v_lshlrev_b32_e32 v106, 16, v100
	v_and_b32_e32 v107, 0xffff0000, v100
	v_lshlrev_b32_e32 v100, 16, v101
	v_and_b32_e32 v101, 0xffff0000, v101
	v_lshl_add_u64 v[102:103], v[138:139], 0, s[24:25]
	v_pk_add_f32 v[98:99], v[98:99], v[100:101]
	v_pk_add_f32 v[96:97], v[96:97], v[106:107]
	v_lshl_add_u64 v[104:105], v[102:103], 1, s[14:15]
	global_store_dwordx4 v[114:115], v[96:99], off offset:576 nt
	s_waitcnt vmcnt(31)
	s_nop 1
	v_mov_b32_e32 v96, v172
	v_mov_b32_e32 v97, v173
	s_nop 0
	v_lshlrev_b32_e32 v100, 16, v96
	v_and_b32_e32 v101, 0xffff0000, v96
	v_lshlrev_b32_e32 v96, 16, v97
	v_and_b32_e32 v97, 0xffff0000, v97
	v_lshl_add_u64 v[98:99], v[102:103], 2, s[4:5]
	v_pk_add_f32 v[94:95], v[94:95], v[96:97]
	v_pk_add_f32 v[92:93], v[92:93], v[100:101]
	global_store_dwordx4 v[98:99], v[92:95], off nt
	s_waitcnt vmcnt(31)
	s_nop 1
	v_mov_b32_e32 v92, v174
	v_mov_b32_e32 v93, v175
	s_nop 0
	v_lshlrev_b32_e32 v94, 16, v92
	v_and_b32_e32 v95, 0xffff0000, v92
	v_lshlrev_b32_e32 v92, 16, v93
	v_and_b32_e32 v93, 0xffff0000, v93
	v_pk_add_f32 v[90:91], v[90:91], v[92:93]
	v_pk_add_f32 v[88:89], v[88:89], v[94:95]
	global_store_dwordx4 v[98:99], v[88:91], off offset:64 nt
	s_waitcnt vmcnt(31)
	s_nop 1
	v_mov_b32_e32 v88, v176
	v_mov_b32_e32 v89, v177
	s_nop 0
	v_lshlrev_b32_e32 v90, 16, v88
	v_and_b32_e32 v91, 0xffff0000, v88
	v_lshlrev_b32_e32 v88, 16, v89
	v_and_b32_e32 v89, 0xffff0000, v89
	v_pk_add_f32 v[86:87], v[86:87], v[88:89]
	v_pk_add_f32 v[84:85], v[84:85], v[90:91]
	global_store_dwordx4 v[98:99], v[84:87], off offset:512 nt
	s_waitcnt vmcnt(31)
	s_nop 1
	v_mov_b32_e32 v84, v178
	v_mov_b32_e32 v85, v179
	s_nop 0
	v_lshlrev_b32_e32 v90, 16, v84
	v_and_b32_e32 v91, 0xffff0000, v84
	v_lshlrev_b32_e32 v84, 16, v85
	v_and_b32_e32 v85, 0xffff0000, v85
	v_lshl_add_u64 v[86:87], v[138:139], 0, s[26:27]
	v_pk_add_f32 v[82:83], v[82:83], v[84:85]
	v_pk_add_f32 v[80:81], v[80:81], v[90:91]
	v_lshl_add_u64 v[88:89], v[86:87], 1, s[14:15]
	global_store_dwordx4 v[98:99], v[80:83], off offset:576 nt
	s_waitcnt vmcnt(31)
	s_nop 1
	v_mov_b32_e32 v80, v180
	v_mov_b32_e32 v81, v181
	s_nop 0
	v_lshlrev_b32_e32 v84, 16, v80
	v_and_b32_e32 v85, 0xffff0000, v80
	v_lshlrev_b32_e32 v80, 16, v81
	v_and_b32_e32 v81, 0xffff0000, v81
	v_lshl_add_u64 v[82:83], v[86:87], 2, s[4:5]
	v_pk_add_f32 v[78:79], v[78:79], v[80:81]
	v_pk_add_f32 v[76:77], v[76:77], v[84:85]
	global_store_dwordx4 v[82:83], v[76:79], off nt
	s_waitcnt vmcnt(31)
	s_nop 1
	v_mov_b32_e32 v76, v182
	v_mov_b32_e32 v77, v183
	s_nop 0
	v_lshlrev_b32_e32 v78, 16, v76
	v_and_b32_e32 v79, 0xffff0000, v76
	v_lshlrev_b32_e32 v76, 16, v77
	v_and_b32_e32 v77, 0xffff0000, v77
	v_pk_add_f32 v[74:75], v[74:75], v[76:77]
	v_pk_add_f32 v[72:73], v[72:73], v[78:79]
	global_store_dwordx4 v[82:83], v[72:75], off offset:64 nt
	s_waitcnt vmcnt(31)
	s_nop 1
	v_mov_b32_e32 v72, v184
	v_mov_b32_e32 v73, v185
	s_nop 0
	v_lshlrev_b32_e32 v74, 16, v72
	v_and_b32_e32 v75, 0xffff0000, v72
	v_lshlrev_b32_e32 v72, 16, v73
	v_and_b32_e32 v73, 0xffff0000, v73
	v_pk_add_f32 v[70:71], v[70:71], v[72:73]
	v_pk_add_f32 v[68:69], v[68:69], v[74:75]
	global_store_dwordx4 v[82:83], v[68:71], off offset:512 nt
	s_waitcnt vmcnt(31)
	s_nop 1
	v_mov_b32_e32 v68, v186
	v_mov_b32_e32 v69, v187
	s_nop 0
	v_lshlrev_b32_e32 v74, 16, v68
	v_and_b32_e32 v75, 0xffff0000, v68
	v_lshlrev_b32_e32 v68, 16, v69
	v_and_b32_e32 v69, 0xffff0000, v69
	v_lshl_add_u64 v[70:71], v[138:139], 0, s[28:29]
	v_pk_add_f32 v[66:67], v[66:67], v[68:69]
	v_pk_add_f32 v[64:65], v[64:65], v[74:75]
	v_lshl_add_u64 v[72:73], v[70:71], 1, s[14:15]
	global_store_dwordx4 v[82:83], v[64:67], off offset:576 nt
	s_waitcnt vmcnt(31)
	s_nop 1
	v_mov_b32_e32 v64, v188
	v_mov_b32_e32 v65, v189
	s_nop 0
	v_lshlrev_b32_e32 v68, 16, v64
	v_and_b32_e32 v69, 0xffff0000, v64
	v_lshlrev_b32_e32 v64, 16, v65
	v_and_b32_e32 v65, 0xffff0000, v65
	v_lshl_add_u64 v[66:67], v[70:71], 2, s[4:5]
	v_pk_add_f32 v[62:63], v[62:63], v[64:65]
	v_pk_add_f32 v[60:61], v[60:61], v[68:69]
	global_store_dwordx4 v[66:67], v[60:63], off nt
	s_waitcnt vmcnt(31)
	s_nop 1
	v_mov_b32_e32 v60, v190
	v_mov_b32_e32 v61, v191
	s_nop 0
	v_lshlrev_b32_e32 v62, 16, v60
	v_and_b32_e32 v63, 0xffff0000, v60
	v_lshlrev_b32_e32 v60, 16, v61
	v_and_b32_e32 v61, 0xffff0000, v61
	v_pk_add_f32 v[58:59], v[58:59], v[60:61]
	v_pk_add_f32 v[56:57], v[56:57], v[62:63]
	global_store_dwordx4 v[66:67], v[56:59], off offset:64 nt
	s_waitcnt vmcnt(31)
	s_nop 1
	v_mov_b32_e32 v56, v192
	v_mov_b32_e32 v57, v193
	s_nop 0
	v_lshlrev_b32_e32 v58, 16, v56
	v_and_b32_e32 v59, 0xffff0000, v56
	v_lshlrev_b32_e32 v56, 16, v57
	v_and_b32_e32 v57, 0xffff0000, v57
	v_pk_add_f32 v[54:55], v[54:55], v[56:57]
	v_pk_add_f32 v[52:53], v[52:53], v[58:59]
	global_store_dwordx4 v[66:67], v[52:55], off offset:512 nt
	s_waitcnt vmcnt(31)
; #define PG8_BAR __builtin_amdgcn_s_barrier()
; template <class Epi, class Sched, bool ALIGN_EPI = false, bool SP2 = false>
; __device__ __forceinline__ void gemm_phase(PG8_LAS unsigned char* lds, const Gemm g, const Sched& S, const Epi& E, const int wid) {
;     ...
;         if constexpr (!Epi::AFTER_DRAIN) { int fr_e = fr, fq_e = fq; asm volatile("" : "+v"(fr_e), "+v"(fq_e)); E(acc, cur, wr, wc, fr_e, fq_e); S.done(cur); }
;         if (!has_next) break;
; #pragma unroll
;         for (int a = 0; a < 2; ++a)
; #pragma unroll
;             for (int b = 0; b < 2; ++b)
; #pragma unroll
;                 for (int m = 0; m < 4; ++m)
; #pragma unroll
;                     for (int n = 0; n < 2; ++n) acc[a][b][m][n] = (f32x4){0.f, 0.f, 0.f, 0.f};
;         cur = nxt; cA = nA; cB = nB; ++ui;
;         if constexpr (ALIGN_EPI) { if (wr == 1) PG8_BAR; }
;     }
	s_nop 1
	v_mov_b32_e32 v52, v194
	v_mov_b32_e32 v53, v195
	s_nop 0
	v_lshlrev_b32_e32 v58, 16, v52
	v_and_b32_e32 v59, 0xffff0000, v52
	v_lshlrev_b32_e32 v52, 16, v53
	v_and_b32_e32 v53, 0xffff0000, v53
	v_lshl_add_u64 v[54:55], v[138:139], 0, s[30:31]
	v_pk_add_f32 v[50:51], v[50:51], v[52:53]
	v_pk_add_f32 v[48:49], v[48:49], v[58:59]
	v_lshl_add_u64 v[56:57], v[54:55], 1, s[14:15]
	global_store_dwordx4 v[66:67], v[48:51], off offset:576 nt
	s_waitcnt vmcnt(31)
	s_nop 1
	v_mov_b32_e32 v48, v196
	v_mov_b32_e32 v49, v197
	s_nop 0
	v_lshlrev_b32_e32 v52, 16, v48
	v_and_b32_e32 v53, 0xffff0000, v48
	v_lshlrev_b32_e32 v48, 16, v49
	v_and_b32_e32 v49, 0xffff0000, v49
	v_lshl_add_u64 v[50:51], v[54:55], 2, s[4:5]
	v_pk_add_f32 v[46:47], v[46:47], v[48:49]
	v_pk_add_f32 v[44:45], v[44:45], v[52:53]
	global_store_dwordx4 v[50:51], v[44:47], off nt
	s_waitcnt vmcnt(31)
	s_nop 1
	v_mov_b32_e32 v44, v198
	v_mov_b32_e32 v45, v199
	s_nop 0
	v_lshlrev_b32_e32 v46, 16, v44
	v_and_b32_e32 v47, 0xffff0000, v44
	v_lshlrev_b32_e32 v44, 16, v45
	v_and_b32_e32 v45, 0xffff0000, v45
	v_pk_add_f32 v[42:43], v[42:43], v[44:45]
	v_pk_add_f32 v[40:41], v[40:41], v[46:47]
	global_store_dwordx4 v[50:51], v[40:43], off offset:64 nt
	s_waitcnt vmcnt(31)
	s_nop 1
	v_mov_b32_e32 v40, v200
	v_mov_b32_e32 v41, v201
	s_nop 0
	v_lshlrev_b32_e32 v42, 16, v40
	v_and_b32_e32 v43, 0xffff0000, v40
	v_lshlrev_b32_e32 v40, 16, v41
	v_and_b32_e32 v41, 0xffff0000, v41
	v_pk_add_f32 v[38:39], v[38:39], v[40:41]
	v_pk_add_f32 v[36:37], v[36:37], v[42:43]
	global_store_dwordx4 v[50:51], v[36:39], off offset:512 nt
	s_waitcnt vmcnt(31)
	s_nop 1
	v_mov_b32_e32 v36, v202
	v_mov_b32_e32 v37, v203
	s_nop 0
	v_lshlrev_b32_e32 v42, 16, v36
	v_and_b32_e32 v43, 0xffff0000, v36
	v_lshlrev_b32_e32 v36, 16, v37
	v_and_b32_e32 v37, 0xffff0000, v37
	v_lshl_add_u64 v[38:39], v[138:139], 0, s[34:35]
	v_pk_add_f32 v[34:35], v[34:35], v[36:37]
	v_pk_add_f32 v[32:33], v[32:33], v[42:43]
	v_lshl_add_u64 v[40:41], v[38:39], 1, s[14:15]
	global_store_dwordx4 v[50:51], v[32:35], off offset:576 nt
	s_waitcnt vmcnt(31)
	s_nop 1
	v_mov_b32_e32 v32, v204
	v_mov_b32_e32 v33, v205
	s_nop 0
	v_lshlrev_b32_e32 v36, 16, v32
	v_and_b32_e32 v37, 0xffff0000, v32
	v_lshlrev_b32_e32 v32, 16, v33
	v_and_b32_e32 v33, 0xffff0000, v33
	v_lshl_add_u64 v[34:35], v[38:39], 2, s[4:5]
	v_pk_add_f32 v[30:31], v[30:31], v[32:33]
	v_pk_add_f32 v[28:29], v[28:29], v[36:37]
	global_store_dwordx4 v[34:35], v[28:31], off nt
	s_waitcnt vmcnt(31)
	s_nop 1
	v_mov_b32_e32 v28, v206
	v_mov_b32_e32 v29, v207
	s_nop 0
	v_lshlrev_b32_e32 v30, 16, v28
	v_and_b32_e32 v31, 0xffff0000, v28
	v_lshlrev_b32_e32 v28, 16, v29
	v_and_b32_e32 v29, 0xffff0000, v29
	v_pk_add_f32 v[26:27], v[26:27], v[28:29]
	v_pk_add_f32 v[24:25], v[24:25], v[30:31]
	global_store_dwordx4 v[34:35], v[24:27], off offset:64 nt
	s_waitcnt vmcnt(31)
	s_nop 1
	v_mov_b32_e32 v24, v208
	v_mov_b32_e32 v25, v209
	s_nop 0
	v_lshlrev_b32_e32 v26, 16, v24
	v_and_b32_e32 v27, 0xffff0000, v24
	v_lshlrev_b32_e32 v24, 16, v25
	v_and_b32_e32 v25, 0xffff0000, v25
	v_pk_add_f32 v[22:23], v[22:23], v[24:25]
	v_pk_add_f32 v[20:21], v[20:21], v[26:27]
	global_store_dwordx4 v[34:35], v[20:23], off offset:512 nt
	s_waitcnt vmcnt(31)
	s_nop 1
	v_mov_b32_e32 v20, v210
	v_mov_b32_e32 v21, v211
	s_nop 0
	v_lshlrev_b32_e32 v26, 16, v20
	v_and_b32_e32 v27, 0xffff0000, v20
	v_lshlrev_b32_e32 v20, 16, v21
	v_and_b32_e32 v21, 0xffff0000, v21
	v_lshl_add_u64 v[22:23], v[138:139], 0, s[36:37]
	v_pk_add_f32 v[18:19], v[18:19], v[20:21]
	v_pk_add_f32 v[16:17], v[16:17], v[26:27]
	v_lshl_add_u64 v[24:25], v[22:23], 1, s[14:15]
	global_store_dwordx4 v[34:35], v[16:19], off offset:576 nt
	s_waitcnt vmcnt(31)
	s_nop 1
	v_mov_b32_e32 v16, v212
	v_mov_b32_e32 v17, v213
	s_nop 0
	v_lshlrev_b32_e32 v20, 16, v16
	v_and_b32_e32 v21, 0xffff0000, v16
	v_lshlrev_b32_e32 v16, 16, v17
	v_and_b32_e32 v17, 0xffff0000, v17
	v_lshl_add_u64 v[18:19], v[22:23], 2, s[4:5]
	v_pk_add_f32 v[14:15], v[14:15], v[16:17]
	v_pk_add_f32 v[12:13], v[12:13], v[20:21]
	global_store_dwordx4 v[18:19], v[12:15], off nt
	s_waitcnt vmcnt(31)
	s_nop 1
	v_mov_b32_e32 v12, v214
	v_mov_b32_e32 v13, v215
	s_nop 0
	v_lshlrev_b32_e32 v14, 16, v12
	v_and_b32_e32 v15, 0xffff0000, v12
	v_lshlrev_b32_e32 v12, 16, v13
	v_and_b32_e32 v13, 0xffff0000, v13
	v_pk_add_f32 v[10:11], v[10:11], v[12:13]
	v_pk_add_f32 v[8:9], v[8:9], v[14:15]
	global_store_dwordx4 v[18:19], v[8:11], off offset:64 nt
	s_waitcnt vmcnt(31)
	s_nop 1
	v_mov_b32_e32 v8, v216
	v_mov_b32_e32 v9, v217
	s_nop 0
	v_lshlrev_b32_e32 v10, 16, v8
	v_and_b32_e32 v11, 0xffff0000, v8
	v_lshlrev_b32_e32 v8, 16, v9
	v_and_b32_e32 v9, 0xffff0000, v9
	v_pk_add_f32 v[6:7], v[6:7], v[8:9]
	v_pk_add_f32 v[4:5], v[4:5], v[10:11]
	global_store_dwordx4 v[18:19], v[4:7], off offset:512 nt
	s_waitcnt vmcnt(31)
	s_nop 1
	v_mov_b32_e32 v4, v218
	v_mov_b32_e32 v5, v219
	s_nop 0
	v_lshlrev_b32_e32 v6, 16, v4
	v_and_b32_e32 v7, 0xffff0000, v4
	v_lshlrev_b32_e32 v4, 16, v5
	v_and_b32_e32 v5, 0xffff0000, v5
	v_pk_add_f32 v[2:3], v[2:3], v[4:5]
	v_pk_add_f32 v[0:1], v[0:1], v[6:7]
	global_store_dwordx4 v[18:19], v[0:3], off offset:576 nt
	s_cbranch_vccnz .LBB0_1565
	s_andn2_b64 vcc, exec, s[12:13]
	s_cbranch_vccnz .LBB0_1564
	s_barrier
	s_branch .LBB0_1564
